# baseline (speedup 1.0000x reference)
.LBB0_223:
	s_and_saveexec_b64 s[90:91], s[0:1]
	s_cbranch_execz .LBB0_231
	v_cmp_lt_i32_e32 vcc, v144, v231
	s_and_saveexec_b64 s[88:89], vcc
	s_cbranch_execz .LBB0_230
	v_add_u32_e32 v0, v15, v152
	ds_read_b128 v[176:179], v0
	ds_read_b128 v[180:183], v0 offset:8704
	ds_read_b128 v[184:187], v0 offset:32
	ds_read_b128 v[196:199], v0 offset:8736
	ds_read_b128 v[200:203], v0 offset:64
	ds_read_b128 v[204:207], v0 offset:8768
	ds_read_b128 v[244:247], v0 offset:96
	ds_read_b128 v[248:251], v0 offset:8800
	v_cmp_gt_i32_e32 vcc, 59, v242
	s_cbranch_vccnz .Lmy_bias_gen
	v_cvt_f32_i32_e32 v0, v242
	v_mul_f32_e32 v188, -2.0, v168
	v_fma_f32 v80, v168, v0, -v2
	v_mul_f32_e32 v0, 0xc1000000, v168
	v_sub_f32_e32 v81, v80, v168
	v_add_f32_e32 v84, v0, v80
	v_add_f32_e32 v85, v0, v81
	v_mul_f32_e32 v189, 0xc1800000, v168
	v_add_f32_e32 v82, v188, v80
	v_add_f32_e32 v83, v188, v81
	v_add_f32_e32 v88, v189, v80
	v_add_f32_e32 v89, v189, v81
	v_add_f32_e32 v92, v189, v84
	v_add_f32_e32 v93, v189, v85
	v_mul_f32_e32 v0, 0xc2000000, v168
	v_add_f32_e32 v86, v188, v84
	v_add_f32_e32 v87, v188, v85
	v_add_f32_e32 v96, v0, v80
	v_add_f32_e32 v97, v0, v81
	v_add_f32_e32 v100, v0, v84
	v_add_f32_e32 v101, v0, v85
	v_add_f32_e32 v104, v0, v88
	v_add_f32_e32 v105, v0, v89
	v_add_f32_e32 v108, v0, v92
	v_add_f32_e32 v109, v0, v93
	v_add_f32_e32 v90, v188, v88
	v_add_f32_e32 v91, v188, v89
	v_add_f32_e32 v94, v188, v92
	v_add_f32_e32 v95, v188, v93
	v_add_f32_e32 v98, v188, v96
	v_add_f32_e32 v99, v188, v97
	v_add_f32_e32 v102, v188, v100
	v_add_f32_e32 v103, v188, v101
	v_add_f32_e32 v106, v188, v104
	v_add_f32_e32 v107, v188, v105
	v_add_f32_e32 v110, v188, v108
	v_add_f32_e32 v111, v188, v109
	s_branch .Lmy_bias_done
